# FFN-in GEMM K loop: static priority raise for the second-arriving wave half (waves 4-7 run a copy of the loop with priorities 2/1 instead of 1/0)
# baseline (speedup 1.0000x reference)
.LBB0_1705:
	s_ashr_i32 s45, s44, 31
	s_lshl_b64 s[12:13], s[44:45], 19
	s_add_u32 s12, s24, s12
	s_addc_u32 s13, s25, s13
	s_and_b64 s[34:35], s[38:39], exec
	s_cselect_b32 s37, s13, s49
	s_cselect_b32 s45, s12, s48
	s_ashr_i32 s41, s40, 31
	s_lshl_b64 s[34:35], s[40:41], 19
	s_add_u32 s34, s1, s34
	s_addc_u32 s35, s10, s35
	s_and_b64 s[50:51], s[38:39], exec
	s_cselect_b32 s41, s35, s27
	s_cselect_b32 s47, s34, s26
	s_add_u32 s48, s48, 0x40080
	s_addc_u32 s49, s49, 0
	s_add_u32 s52, s26, 0x100
	v_mov_b32_e32 v0, 0
	s_addc_u32 s53, s27, 0
	s_mov_b32 s64, -2
	v_mov_b32_e32 v1, v0
	v_mov_b32_e32 v2, v0
	v_mov_b32_e32 v3, v0
	v_mov_b32_e32 v8, v0
	v_mov_b32_e32 v9, v0
	v_mov_b32_e32 v10, v0
	v_mov_b32_e32 v11, v0
	v_mov_b32_e32 v16, v0
	v_mov_b32_e32 v17, v0
	v_mov_b32_e32 v18, v0
	v_mov_b32_e32 v19, v0
	v_mov_b32_e32 v24, v0
	v_mov_b32_e32 v25, v0
	v_mov_b32_e32 v26, v0
	v_mov_b32_e32 v27, v0
	v_mov_b32_e32 v32, v0
	v_mov_b32_e32 v33, v0
	v_mov_b32_e32 v34, v0
	v_mov_b32_e32 v35, v0
	v_mov_b32_e32 v40, v0
	v_mov_b32_e32 v41, v0
	v_mov_b32_e32 v42, v0
	v_mov_b32_e32 v43, v0
	v_mov_b32_e32 v52, v0
	v_mov_b32_e32 v53, v0
	v_mov_b32_e32 v54, v0
	v_mov_b32_e32 v55, v0
	v_mov_b32_e32 v60, v0
	v_mov_b32_e32 v61, v0
	v_mov_b32_e32 v62, v0
	v_mov_b32_e32 v63, v0
	v_mov_b32_e32 v4, v0
	v_mov_b32_e32 v5, v0
	v_mov_b32_e32 v6, v0
	v_mov_b32_e32 v7, v0
	v_mov_b32_e32 v12, v0
	v_mov_b32_e32 v13, v0
	v_mov_b32_e32 v14, v0
	v_mov_b32_e32 v15, v0
	v_mov_b32_e32 v20, v0
	v_mov_b32_e32 v21, v0
	v_mov_b32_e32 v22, v0
	v_mov_b32_e32 v23, v0
	v_mov_b32_e32 v28, v0
	v_mov_b32_e32 v29, v0
	v_mov_b32_e32 v30, v0
	v_mov_b32_e32 v31, v0
	v_mov_b32_e32 v36, v0
	v_mov_b32_e32 v37, v0
	v_mov_b32_e32 v38, v0
	v_mov_b32_e32 v39, v0
	v_mov_b32_e32 v44, v0
	v_mov_b32_e32 v45, v0
	v_mov_b32_e32 v46, v0
	v_mov_b32_e32 v47, v0
	v_mov_b32_e32 v56, v0
	v_mov_b32_e32 v57, v0
	v_mov_b32_e32 v58, v0
	v_mov_b32_e32 v59, v0
	v_mov_b32_e32 v64, v0
	v_mov_b32_e32 v65, v0
	v_mov_b32_e32 v66, v0
	v_mov_b32_e32 v67, v0
	v_mov_b32_e32 v68, v0
	v_mov_b32_e32 v69, v0
	v_mov_b32_e32 v70, v0
	v_mov_b32_e32 v71, v0
	v_mov_b32_e32 v76, v0
	v_mov_b32_e32 v77, v0
	v_mov_b32_e32 v78, v0
	v_mov_b32_e32 v79, v0
	v_mov_b32_e32 v84, v0
	v_mov_b32_e32 v85, v0
	v_mov_b32_e32 v86, v0
	v_mov_b32_e32 v87, v0
	v_mov_b32_e32 v92, v0
	v_mov_b32_e32 v93, v0
	v_mov_b32_e32 v94, v0
	v_mov_b32_e32 v95, v0
	v_mov_b32_e32 v100, v0
	v_mov_b32_e32 v101, v0
	v_mov_b32_e32 v102, v0
	v_mov_b32_e32 v103, v0
	v_mov_b32_e32 v108, v0
	v_mov_b32_e32 v109, v0
	v_mov_b32_e32 v110, v0
	v_mov_b32_e32 v111, v0
	v_mov_b32_e32 v116, v0
	v_mov_b32_e32 v117, v0
	v_mov_b32_e32 v118, v0
	v_mov_b32_e32 v119, v0
	v_mov_b32_e32 v124, v0
	v_mov_b32_e32 v125, v0
	v_mov_b32_e32 v126, v0
	v_mov_b32_e32 v127, v0
	v_mov_b32_e32 v72, v0
	v_mov_b32_e32 v73, v0
	v_mov_b32_e32 v74, v0
	v_mov_b32_e32 v75, v0
	v_mov_b32_e32 v80, v0
	v_mov_b32_e32 v81, v0
	v_mov_b32_e32 v82, v0
	v_mov_b32_e32 v83, v0
	v_mov_b32_e32 v88, v0
	v_mov_b32_e32 v89, v0
	v_mov_b32_e32 v90, v0
	v_mov_b32_e32 v91, v0
	v_mov_b32_e32 v96, v0
	v_mov_b32_e32 v97, v0
	v_mov_b32_e32 v98, v0
	v_mov_b32_e32 v99, v0
	v_mov_b32_e32 v104, v0
	v_mov_b32_e32 v105, v0
	v_mov_b32_e32 v106, v0
	v_mov_b32_e32 v107, v0
	v_mov_b32_e32 v112, v0
	v_mov_b32_e32 v113, v0
	v_mov_b32_e32 v114, v0
	v_mov_b32_e32 v115, v0
	v_mov_b32_e32 v120, v0
	v_mov_b32_e32 v121, v0
	v_mov_b32_e32 v122, v0
	v_mov_b32_e32 v123, v0
	v_mov_b32_e32 v128, v0
	v_mov_b32_e32 v129, v0
	v_mov_b32_e32 v130, v0
	v_mov_b32_e32 v131, v0
	s_and_b64 vcc, exec, s[6:7]
	s_cbranch_vccz .Lgk2_1706
.LBB0_1706:
	s_add_u32 s26, s48, 0xfffc0080
	s_addc_u32 s27, s49, -1
	s_add_i32 s65, 0, 0x10000
	s_cmp_eq_u32 s64, 12
	s_cselect_b32 s51, s37, s27
	s_cselect_b32 s50, s45, s26
	s_cselect_b32 s27, s41, s53
	s_cselect_b32 s26, s47, s52
	s_add_i32 s74, 0, 0x14000
	v_add_u32_e32 v154, s65, v140
	v_add_u32_e32 v170, s74, v140
	ds_read_b128 v[142:145], v154
	ds_read_b128 v[146:149], v154 offset:1024
	ds_read_b128 v[150:153], v154 offset:2048
	ds_read_b128 v[154:157], v154 offset:3072
	ds_read_b128 v[158:161], v170
	ds_read_b128 v[162:165], v170 offset:1024
	ds_read_b128 v[166:169], v170 offset:2048
	ds_read_b128 v[170:173], v170 offset:3072
	v_lshl_add_u64 v[182:183], s[48:49], 0, v[136:137]
	s_add_i32 m0, s15, 0xc000
	ds_read_b128 v[174:177], v141
	ds_read_b128 v[178:181], v141 offset:1024
	ds_read_b128 v[196:199], v141 offset:2048
	ds_read_b128 v[200:203], v141 offset:3072
	ds_read_b128 v[204:207], v141 offset:4096
	ds_read_b128 v[208:211], v141 offset:5120
	ds_read_b128 v[212:215], v141 offset:6144
	ds_read_b128 v[216:219], v141 offset:7168
	global_load_lds_dwordx4 v[182:183], off
	v_lshl_add_u64 v[182:183], s[48:49], 0, v[138:139]
	s_add_i32 m0, s15, 0xe000
	s_nop 0
	global_load_lds_dwordx4 v[182:183], off
	s_waitcnt vmcnt(8)
	s_waitcnt lgkmcnt(0)
	s_barrier
	s_setprio 1
	s_waitcnt lgkmcnt(0)
	v_mfma_f32_16x16x32_bf16 v[128:131], v[142:145], v[174:177], v[128:131]
	v_mfma_f32_16x16x32_bf16 v[120:123], v[150:153], v[174:177], v[120:123]
	v_mfma_f32_16x16x32_bf16 v[112:115], v[142:145], v[196:199], v[112:115]
	v_mfma_f32_16x16x32_bf16 v[104:107], v[150:153], v[196:199], v[104:107]
	v_mfma_f32_16x16x32_bf16 v[96:99], v[142:145], v[204:207], v[96:99]
	v_mfma_f32_16x16x32_bf16 v[88:91], v[150:153], v[204:207], v[88:91]
	v_mfma_f32_16x16x32_bf16 v[80:83], v[142:145], v[212:215], v[80:83]
	v_mfma_f32_16x16x32_bf16 v[72:75], v[150:153], v[212:215], v[72:75]
	v_mfma_f32_16x16x32_bf16 v[128:131], v[146:149], v[178:181], v[128:131]
	v_mfma_f32_16x16x32_bf16 v[120:123], v[154:157], v[178:181], v[120:123]
	v_mfma_f32_16x16x32_bf16 v[112:115], v[146:149], v[200:203], v[112:115]
	v_mfma_f32_16x16x32_bf16 v[104:107], v[154:157], v[200:203], v[104:107]
	v_mfma_f32_16x16x32_bf16 v[96:99], v[146:149], v[208:211], v[96:99]
	v_mfma_f32_16x16x32_bf16 v[88:91], v[154:157], v[208:211], v[88:91]
	v_mfma_f32_16x16x32_bf16 v[80:83], v[146:149], v[216:219], v[80:83]
	v_mfma_f32_16x16x32_bf16 v[72:75], v[154:157], v[216:219], v[72:75]
	s_setprio 0
	s_setprio 1
	v_mfma_f32_16x16x32_bf16 v[124:127], v[158:161], v[174:177], v[124:127]
	v_mfma_f32_16x16x32_bf16 v[116:119], v[166:169], v[174:177], v[116:119]
	v_mfma_f32_16x16x32_bf16 v[108:111], v[158:161], v[196:199], v[108:111]
	v_mfma_f32_16x16x32_bf16 v[100:103], v[166:169], v[196:199], v[100:103]
	v_mfma_f32_16x16x32_bf16 v[92:95], v[158:161], v[204:207], v[92:95]
	v_mfma_f32_16x16x32_bf16 v[84:87], v[166:169], v[204:207], v[84:87]
	v_mfma_f32_16x16x32_bf16 v[76:79], v[158:161], v[212:215], v[76:79]
	v_mfma_f32_16x16x32_bf16 v[68:71], v[166:169], v[212:215], v[68:71]
	v_mfma_f32_16x16x32_bf16 v[124:127], v[162:165], v[178:181], v[124:127]
	v_mfma_f32_16x16x32_bf16 v[116:119], v[170:173], v[178:181], v[116:119]
	v_mfma_f32_16x16x32_bf16 v[108:111], v[162:165], v[200:203], v[108:111]
	v_mfma_f32_16x16x32_bf16 v[100:103], v[170:173], v[200:203], v[100:103]
	v_mfma_f32_16x16x32_bf16 v[92:95], v[162:165], v[208:211], v[92:95]
	v_mfma_f32_16x16x32_bf16 v[84:87], v[170:173], v[208:211], v[84:87]
	v_mfma_f32_16x16x32_bf16 v[76:79], v[162:165], v[216:219], v[76:79]
	v_mfma_f32_16x16x32_bf16 v[68:71], v[170:173], v[216:219], v[68:71]
	s_setprio 0
	s_barrier
	s_add_i32 s65, s65, s11
	v_lshl_add_u64 v[182:183], s[26:27], 0, v[50:51]
	s_mov_b32 m0, s65
	ds_read_b128 v[174:177], v141 offset:16384
	ds_read_b128 v[178:181], v141 offset:17408
	ds_read_b128 v[196:199], v141 offset:18432
	ds_read_b128 v[200:203], v141 offset:19456
	ds_read_b128 v[204:207], v141 offset:20480
	ds_read_b128 v[208:211], v141 offset:21504
	ds_read_b128 v[212:215], v141 offset:22528
	ds_read_b128 v[216:219], v141 offset:23552
	global_load_lds_dwordx4 v[182:183], off
	s_add_i32 m0, s65, 0x2000
	s_add_u32 s72, s26, 0x40000
	v_lshl_add_u64 v[220:221], s[26:27], 0, v[48:49]
	s_addc_u32 s73, s27, 0
	s_add_i32 s65, s74, s11
	global_load_lds_dwordx4 v[220:221], off
	v_lshl_add_u64 v[222:223], s[72:73], 0, v[50:51]
	s_mov_b32 m0, s65
	v_lshl_add_u64 v[224:225], s[50:51], 0, v[132:133]
	global_load_lds_dwordx4 v[222:223], off
	v_lshl_add_u64 v[222:223], s[72:73], 0, v[48:49]
	s_add_i32 m0, s65, 0x2000
	s_nop 0
	global_load_lds_dwordx4 v[222:223], off
	v_lshl_add_u64 v[222:223], s[50:51], 0, v[134:135]
	s_mov_b32 m0, s15
	s_nop 0
	global_load_lds_dwordx4 v[222:223], off
	s_mov_b32 m0, s16
	s_nop 0
	global_load_lds_dwordx4 v[224:225], off
	s_waitcnt vmcnt(8)
	s_waitcnt lgkmcnt(0)
	s_barrier
	s_setprio 1
	s_waitcnt lgkmcnt(0)
	v_mfma_f32_16x16x32_bf16 v[64:67], v[142:145], v[174:177], v[64:67]
	v_mfma_f32_16x16x32_bf16 v[56:59], v[150:153], v[174:177], v[56:59]
	v_mfma_f32_16x16x32_bf16 v[44:47], v[142:145], v[196:199], v[44:47]
	v_mfma_f32_16x16x32_bf16 v[36:39], v[150:153], v[196:199], v[36:39]
	v_mfma_f32_16x16x32_bf16 v[28:31], v[142:145], v[204:207], v[28:31]
	v_mfma_f32_16x16x32_bf16 v[20:23], v[150:153], v[204:207], v[20:23]
	v_mfma_f32_16x16x32_bf16 v[12:15], v[142:145], v[212:215], v[12:15]
	v_mfma_f32_16x16x32_bf16 v[4:7], v[150:153], v[212:215], v[4:7]
	v_mfma_f32_16x16x32_bf16 v[64:67], v[146:149], v[178:181], v[64:67]
	v_mfma_f32_16x16x32_bf16 v[56:59], v[154:157], v[178:181], v[56:59]
	v_mfma_f32_16x16x32_bf16 v[44:47], v[146:149], v[200:203], v[44:47]
	v_mfma_f32_16x16x32_bf16 v[36:39], v[154:157], v[200:203], v[36:39]
	v_mfma_f32_16x16x32_bf16 v[28:31], v[146:149], v[208:211], v[28:31]
	v_mfma_f32_16x16x32_bf16 v[20:23], v[154:157], v[208:211], v[20:23]
	v_mfma_f32_16x16x32_bf16 v[12:15], v[146:149], v[216:219], v[12:15]
	v_mfma_f32_16x16x32_bf16 v[4:7], v[154:157], v[216:219], v[4:7]
	s_setprio 0
	s_setprio 1
	v_mfma_f32_16x16x32_bf16 v[60:63], v[158:161], v[174:177], v[60:63]
	v_mfma_f32_16x16x32_bf16 v[52:55], v[166:169], v[174:177], v[52:55]
	v_mfma_f32_16x16x32_bf16 v[40:43], v[158:161], v[196:199], v[40:43]
	v_mfma_f32_16x16x32_bf16 v[32:35], v[166:169], v[196:199], v[32:35]
	v_mfma_f32_16x16x32_bf16 v[24:27], v[158:161], v[204:207], v[24:27]
	v_mfma_f32_16x16x32_bf16 v[16:19], v[166:169], v[204:207], v[16:19]
	v_mfma_f32_16x16x32_bf16 v[8:11], v[158:161], v[212:215], v[8:11]
	v_mfma_f32_16x16x32_bf16 v[0:3], v[166:169], v[212:215], v[0:3]
	v_mfma_f32_16x16x32_bf16 v[60:63], v[162:165], v[178:181], v[60:63]
	v_mfma_f32_16x16x32_bf16 v[52:55], v[170:173], v[178:181], v[52:55]
	v_mfma_f32_16x16x32_bf16 v[40:43], v[162:165], v[200:203], v[40:43]
	v_mfma_f32_16x16x32_bf16 v[32:35], v[170:173], v[200:203], v[32:35]
	v_mfma_f32_16x16x32_bf16 v[24:27], v[162:165], v[208:211], v[24:27]
	v_mfma_f32_16x16x32_bf16 v[16:19], v[170:173], v[208:211], v[16:19]
	v_mfma_f32_16x16x32_bf16 v[8:11], v[162:165], v[216:219], v[8:11]
	v_mfma_f32_16x16x32_bf16 v[0:3], v[170:173], v[216:219], v[0:3]
	s_setprio 0
	s_barrier
	s_add_i32 s65, 0, 0x18000
	s_add_i32 s72, 0, 0x1c000
	v_add_u32_e32 v154, s65, v140
	v_add_u32_e32 v170, s72, v140
	ds_read_b128 v[142:145], v154
	ds_read_b128 v[146:149], v154 offset:1024
	ds_read_b128 v[150:153], v154 offset:2048
	ds_read_b128 v[154:157], v154 offset:3072
	ds_read_b128 v[158:161], v170
	ds_read_b128 v[162:165], v170 offset:1024
	ds_read_b128 v[166:169], v170 offset:2048
	ds_read_b128 v[170:173], v170 offset:3072
	s_add_u32 s50, s50, 0x40000
	s_addc_u32 s51, s51, 0
	s_mov_b32 m0, s17
	v_lshl_add_u64 v[226:227], s[50:51], 0, v[134:135]
	ds_read_b128 v[174:177], v141 offset:32768
	ds_read_b128 v[178:181], v141 offset:33792
	ds_read_b128 v[196:199], v141 offset:34816
	ds_read_b128 v[200:203], v141 offset:35840
	ds_read_b128 v[204:207], v141 offset:36864
	ds_read_b128 v[208:211], v141 offset:37888
	ds_read_b128 v[212:215], v141 offset:38912
	ds_read_b128 v[216:219], v141 offset:39936
	global_load_lds_dwordx4 v[226:227], off
	v_lshl_add_u64 v[226:227], s[50:51], 0, v[132:133]
	s_mov_b32 m0, s18
	s_nop 0
	global_load_lds_dwordx4 v[226:227], off
	s_waitcnt vmcnt(8)
	s_waitcnt lgkmcnt(0)
	s_barrier
	s_setprio 1
	s_waitcnt lgkmcnt(0)
	v_mfma_f32_16x16x32_bf16 v[128:131], v[142:145], v[174:177], v[128:131]
	v_mfma_f32_16x16x32_bf16 v[120:123], v[150:153], v[174:177], v[120:123]
	v_mfma_f32_16x16x32_bf16 v[112:115], v[142:145], v[196:199], v[112:115]
	v_mfma_f32_16x16x32_bf16 v[104:107], v[150:153], v[196:199], v[104:107]
	v_mfma_f32_16x16x32_bf16 v[96:99], v[142:145], v[204:207], v[96:99]
	v_mfma_f32_16x16x32_bf16 v[88:91], v[150:153], v[204:207], v[88:91]
	v_mfma_f32_16x16x32_bf16 v[80:83], v[142:145], v[212:215], v[80:83]
	v_mfma_f32_16x16x32_bf16 v[72:75], v[150:153], v[212:215], v[72:75]
	v_mfma_f32_16x16x32_bf16 v[128:131], v[146:149], v[178:181], v[128:131]
	v_mfma_f32_16x16x32_bf16 v[120:123], v[154:157], v[178:181], v[120:123]
	v_mfma_f32_16x16x32_bf16 v[112:115], v[146:149], v[200:203], v[112:115]
	v_mfma_f32_16x16x32_bf16 v[104:107], v[154:157], v[200:203], v[104:107]
	v_mfma_f32_16x16x32_bf16 v[96:99], v[146:149], v[208:211], v[96:99]
	v_mfma_f32_16x16x32_bf16 v[88:91], v[154:157], v[208:211], v[88:91]
	v_mfma_f32_16x16x32_bf16 v[80:83], v[146:149], v[216:219], v[80:83]
	v_mfma_f32_16x16x32_bf16 v[72:75], v[154:157], v[216:219], v[72:75]
	s_setprio 0
	s_setprio 1
	v_mfma_f32_16x16x32_bf16 v[124:127], v[158:161], v[174:177], v[124:127]
	v_mfma_f32_16x16x32_bf16 v[116:119], v[166:169], v[174:177], v[116:119]
	v_mfma_f32_16x16x32_bf16 v[108:111], v[158:161], v[196:199], v[108:111]
	v_mfma_f32_16x16x32_bf16 v[100:103], v[166:169], v[196:199], v[100:103]
	v_mfma_f32_16x16x32_bf16 v[92:95], v[158:161], v[204:207], v[92:95]
	v_mfma_f32_16x16x32_bf16 v[84:87], v[166:169], v[204:207], v[84:87]
	v_mfma_f32_16x16x32_bf16 v[76:79], v[158:161], v[212:215], v[76:79]
	v_mfma_f32_16x16x32_bf16 v[68:71], v[166:169], v[212:215], v[68:71]
	v_mfma_f32_16x16x32_bf16 v[124:127], v[162:165], v[178:181], v[124:127]
	v_mfma_f32_16x16x32_bf16 v[116:119], v[170:173], v[178:181], v[116:119]
	v_mfma_f32_16x16x32_bf16 v[108:111], v[162:165], v[200:203], v[108:111]
	v_mfma_f32_16x16x32_bf16 v[100:103], v[170:173], v[200:203], v[100:103]
	v_mfma_f32_16x16x32_bf16 v[92:95], v[162:165], v[208:211], v[92:95]
	v_mfma_f32_16x16x32_bf16 v[84:87], v[170:173], v[208:211], v[84:87]
	v_mfma_f32_16x16x32_bf16 v[76:79], v[162:165], v[216:219], v[76:79]
	v_mfma_f32_16x16x32_bf16 v[68:71], v[170:173], v[216:219], v[68:71]
	s_setprio 0
	s_barrier
	s_add_i32 s50, s65, s11
	v_lshl_add_u64 v[182:183], v[182:183], 0, s[58:59]
	s_mov_b32 m0, s50
	ds_read_b128 v[174:177], v141 offset:49152
	ds_read_b128 v[178:181], v141 offset:50176
	ds_read_b128 v[196:199], v141 offset:51200
	ds_read_b128 v[200:203], v141 offset:52224
	ds_read_b128 v[204:207], v141 offset:53248
	ds_read_b128 v[208:211], v141 offset:54272
	ds_read_b128 v[212:215], v141 offset:55296
	ds_read_b128 v[216:219], v141 offset:56320
	global_load_lds_dwordx4 v[182:183], off
	s_add_i32 m0, s50, 0x2000
	s_add_u32 s26, s26, 0x40080
	v_lshl_add_u64 v[182:183], v[220:221], 0, s[58:59]
	s_addc_u32 s27, s27, 0
	s_add_i32 s50, s72, s11
	global_load_lds_dwordx4 v[182:183], off
	v_lshl_add_u64 v[182:183], s[26:27], 0, v[50:51]
	s_mov_b32 m0, s50
	s_nop 0
	global_load_lds_dwordx4 v[182:183], off
	v_lshl_add_u64 v[182:183], s[26:27], 0, v[48:49]
	s_add_i32 m0, s50, 0x2000
	s_nop 0
	global_load_lds_dwordx4 v[182:183], off
	v_lshl_add_u64 v[182:183], v[222:223], 0, s[58:59]
	s_mov_b32 m0, s21
	s_nop 0
	global_load_lds_dwordx4 v[182:183], off
	v_lshl_add_u64 v[182:183], v[224:225], 0, s[58:59]
	s_mov_b32 m0, s22
	s_nop 0
	global_load_lds_dwordx4 v[182:183], off
	s_waitcnt vmcnt(8)
	s_waitcnt lgkmcnt(0)
	s_barrier
	s_setprio 1
	s_waitcnt lgkmcnt(0)
	v_mfma_f32_16x16x32_bf16 v[64:67], v[142:145], v[174:177], v[64:67]
	v_mfma_f32_16x16x32_bf16 v[56:59], v[150:153], v[174:177], v[56:59]
	v_mfma_f32_16x16x32_bf16 v[44:47], v[142:145], v[196:199], v[44:47]
	v_mfma_f32_16x16x32_bf16 v[36:39], v[150:153], v[196:199], v[36:39]
	v_mfma_f32_16x16x32_bf16 v[28:31], v[142:145], v[204:207], v[28:31]
	v_mfma_f32_16x16x32_bf16 v[20:23], v[150:153], v[204:207], v[20:23]
	v_mfma_f32_16x16x32_bf16 v[12:15], v[142:145], v[212:215], v[12:15]
	v_mfma_f32_16x16x32_bf16 v[4:7], v[150:153], v[212:215], v[4:7]
	v_mfma_f32_16x16x32_bf16 v[64:67], v[146:149], v[178:181], v[64:67]
	v_mfma_f32_16x16x32_bf16 v[56:59], v[154:157], v[178:181], v[56:59]
	v_mfma_f32_16x16x32_bf16 v[44:47], v[146:149], v[200:203], v[44:47]
	v_mfma_f32_16x16x32_bf16 v[36:39], v[154:157], v[200:203], v[36:39]
	v_mfma_f32_16x16x32_bf16 v[28:31], v[146:149], v[208:211], v[28:31]
	v_mfma_f32_16x16x32_bf16 v[20:23], v[154:157], v[208:211], v[20:23]
	v_mfma_f32_16x16x32_bf16 v[12:15], v[146:149], v[216:219], v[12:15]
	v_mfma_f32_16x16x32_bf16 v[4:7], v[154:157], v[216:219], v[4:7]
	s_setprio 0
	s_setprio 1
	v_mfma_f32_16x16x32_bf16 v[60:63], v[158:161], v[174:177], v[60:63]
	v_mfma_f32_16x16x32_bf16 v[52:55], v[166:169], v[174:177], v[52:55]
	v_mfma_f32_16x16x32_bf16 v[40:43], v[158:161], v[196:199], v[40:43]
	v_mfma_f32_16x16x32_bf16 v[32:35], v[166:169], v[196:199], v[32:35]
	v_mfma_f32_16x16x32_bf16 v[24:27], v[158:161], v[204:207], v[24:27]
	v_mfma_f32_16x16x32_bf16 v[16:19], v[166:169], v[204:207], v[16:19]
	v_mfma_f32_16x16x32_bf16 v[8:11], v[158:161], v[212:215], v[8:11]
	v_mfma_f32_16x16x32_bf16 v[0:3], v[166:169], v[212:215], v[0:3]
	v_mfma_f32_16x16x32_bf16 v[60:63], v[162:165], v[178:181], v[60:63]
	v_mfma_f32_16x16x32_bf16 v[52:55], v[170:173], v[178:181], v[52:55]
	v_mfma_f32_16x16x32_bf16 v[40:43], v[162:165], v[200:203], v[40:43]
	v_mfma_f32_16x16x32_bf16 v[32:35], v[170:173], v[200:203], v[32:35]
	v_mfma_f32_16x16x32_bf16 v[24:27], v[162:165], v[208:211], v[24:27]
	v_mfma_f32_16x16x32_bf16 v[16:19], v[170:173], v[208:211], v[16:19]
	v_mfma_f32_16x16x32_bf16 v[8:11], v[162:165], v[216:219], v[8:11]
	v_mfma_f32_16x16x32_bf16 v[0:3], v[170:173], v[216:219], v[0:3]
	s_setprio 0
	s_barrier
	s_add_i32 s64, s64, 2
	s_add_u32 s48, s48, 0x100
	s_addc_u32 s49, s49, 0
	s_add_u32 s52, s52, 0x100
	s_addc_u32 s53, s53, 0
	s_cmp_gt_u32 s64, 13
	s_cbranch_scc0 .LBB0_1706
	s_branch .Lgk_join
.Lgk2_1706:
	s_add_u32 s26, s48, 0xfffc0080
	s_addc_u32 s27, s49, -1
	s_add_i32 s65, 0, 0x10000
	s_cmp_eq_u32 s64, 12
	s_cselect_b32 s51, s37, s27
	s_cselect_b32 s50, s45, s26
	s_cselect_b32 s27, s41, s53
	s_cselect_b32 s26, s47, s52
	s_add_i32 s74, 0, 0x14000
	v_add_u32_e32 v154, s65, v140
	v_add_u32_e32 v170, s74, v140
	ds_read_b128 v[142:145], v154
	ds_read_b128 v[146:149], v154 offset:1024
	ds_read_b128 v[150:153], v154 offset:2048
	ds_read_b128 v[154:157], v154 offset:3072
	ds_read_b128 v[158:161], v170
	ds_read_b128 v[162:165], v170 offset:1024
	ds_read_b128 v[166:169], v170 offset:2048
	ds_read_b128 v[170:173], v170 offset:3072
	v_lshl_add_u64 v[182:183], s[48:49], 0, v[136:137]
	s_add_i32 m0, s15, 0xc000
	ds_read_b128 v[174:177], v141
	ds_read_b128 v[178:181], v141 offset:1024
	ds_read_b128 v[196:199], v141 offset:2048
	ds_read_b128 v[200:203], v141 offset:3072
	ds_read_b128 v[204:207], v141 offset:4096
	ds_read_b128 v[208:211], v141 offset:5120
	ds_read_b128 v[212:215], v141 offset:6144
	ds_read_b128 v[216:219], v141 offset:7168
	global_load_lds_dwordx4 v[182:183], off
	v_lshl_add_u64 v[182:183], s[48:49], 0, v[138:139]
	s_add_i32 m0, s15, 0xe000
	s_nop 0
	global_load_lds_dwordx4 v[182:183], off
	s_waitcnt vmcnt(8)
	s_waitcnt lgkmcnt(0)
	s_barrier
	s_setprio 2
	s_waitcnt lgkmcnt(0)
	v_mfma_f32_16x16x32_bf16 v[128:131], v[142:145], v[174:177], v[128:131]
	v_mfma_f32_16x16x32_bf16 v[120:123], v[150:153], v[174:177], v[120:123]
	v_mfma_f32_16x16x32_bf16 v[112:115], v[142:145], v[196:199], v[112:115]
	v_mfma_f32_16x16x32_bf16 v[104:107], v[150:153], v[196:199], v[104:107]
	v_mfma_f32_16x16x32_bf16 v[96:99], v[142:145], v[204:207], v[96:99]
	v_mfma_f32_16x16x32_bf16 v[88:91], v[150:153], v[204:207], v[88:91]
	v_mfma_f32_16x16x32_bf16 v[80:83], v[142:145], v[212:215], v[80:83]
	v_mfma_f32_16x16x32_bf16 v[72:75], v[150:153], v[212:215], v[72:75]
	v_mfma_f32_16x16x32_bf16 v[128:131], v[146:149], v[178:181], v[128:131]
	v_mfma_f32_16x16x32_bf16 v[120:123], v[154:157], v[178:181], v[120:123]
	v_mfma_f32_16x16x32_bf16 v[112:115], v[146:149], v[200:203], v[112:115]
	v_mfma_f32_16x16x32_bf16 v[104:107], v[154:157], v[200:203], v[104:107]
	v_mfma_f32_16x16x32_bf16 v[96:99], v[146:149], v[208:211], v[96:99]
	v_mfma_f32_16x16x32_bf16 v[88:91], v[154:157], v[208:211], v[88:91]
	v_mfma_f32_16x16x32_bf16 v[80:83], v[146:149], v[216:219], v[80:83]
	v_mfma_f32_16x16x32_bf16 v[72:75], v[154:157], v[216:219], v[72:75]
	s_setprio 1
	s_setprio 2
	v_mfma_f32_16x16x32_bf16 v[124:127], v[158:161], v[174:177], v[124:127]
	v_mfma_f32_16x16x32_bf16 v[116:119], v[166:169], v[174:177], v[116:119]
	v_mfma_f32_16x16x32_bf16 v[108:111], v[158:161], v[196:199], v[108:111]
	v_mfma_f32_16x16x32_bf16 v[100:103], v[166:169], v[196:199], v[100:103]
	v_mfma_f32_16x16x32_bf16 v[92:95], v[158:161], v[204:207], v[92:95]
	v_mfma_f32_16x16x32_bf16 v[84:87], v[166:169], v[204:207], v[84:87]
	v_mfma_f32_16x16x32_bf16 v[76:79], v[158:161], v[212:215], v[76:79]
	v_mfma_f32_16x16x32_bf16 v[68:71], v[166:169], v[212:215], v[68:71]
	v_mfma_f32_16x16x32_bf16 v[124:127], v[162:165], v[178:181], v[124:127]
	v_mfma_f32_16x16x32_bf16 v[116:119], v[170:173], v[178:181], v[116:119]
	v_mfma_f32_16x16x32_bf16 v[108:111], v[162:165], v[200:203], v[108:111]
	v_mfma_f32_16x16x32_bf16 v[100:103], v[170:173], v[200:203], v[100:103]
	v_mfma_f32_16x16x32_bf16 v[92:95], v[162:165], v[208:211], v[92:95]
	v_mfma_f32_16x16x32_bf16 v[84:87], v[170:173], v[208:211], v[84:87]
	v_mfma_f32_16x16x32_bf16 v[76:79], v[162:165], v[216:219], v[76:79]
	v_mfma_f32_16x16x32_bf16 v[68:71], v[170:173], v[216:219], v[68:71]
	s_setprio 1
	s_barrier
	s_add_i32 s65, s65, s11
	v_lshl_add_u64 v[182:183], s[26:27], 0, v[50:51]
	s_mov_b32 m0, s65
	ds_read_b128 v[174:177], v141 offset:16384
	ds_read_b128 v[178:181], v141 offset:17408
	ds_read_b128 v[196:199], v141 offset:18432
	ds_read_b128 v[200:203], v141 offset:19456
	ds_read_b128 v[204:207], v141 offset:20480
	ds_read_b128 v[208:211], v141 offset:21504
	ds_read_b128 v[212:215], v141 offset:22528
	ds_read_b128 v[216:219], v141 offset:23552
	global_load_lds_dwordx4 v[182:183], off
	s_add_i32 m0, s65, 0x2000
	s_add_u32 s72, s26, 0x40000
	v_lshl_add_u64 v[220:221], s[26:27], 0, v[48:49]
	s_addc_u32 s73, s27, 0
	s_add_i32 s65, s74, s11
	global_load_lds_dwordx4 v[220:221], off
	v_lshl_add_u64 v[222:223], s[72:73], 0, v[50:51]
	s_mov_b32 m0, s65
	v_lshl_add_u64 v[224:225], s[50:51], 0, v[132:133]
	global_load_lds_dwordx4 v[222:223], off
	v_lshl_add_u64 v[222:223], s[72:73], 0, v[48:49]
	s_add_i32 m0, s65, 0x2000
	s_nop 0
	global_load_lds_dwordx4 v[222:223], off
	v_lshl_add_u64 v[222:223], s[50:51], 0, v[134:135]
	s_mov_b32 m0, s15
	s_nop 0
	global_load_lds_dwordx4 v[222:223], off
	s_mov_b32 m0, s16
	s_nop 0
	global_load_lds_dwordx4 v[224:225], off
	s_waitcnt vmcnt(8)
	s_waitcnt lgkmcnt(0)
	s_barrier
	s_setprio 2
	s_waitcnt lgkmcnt(0)
	v_mfma_f32_16x16x32_bf16 v[64:67], v[142:145], v[174:177], v[64:67]
	v_mfma_f32_16x16x32_bf16 v[56:59], v[150:153], v[174:177], v[56:59]
	v_mfma_f32_16x16x32_bf16 v[44:47], v[142:145], v[196:199], v[44:47]
	v_mfma_f32_16x16x32_bf16 v[36:39], v[150:153], v[196:199], v[36:39]
	v_mfma_f32_16x16x32_bf16 v[28:31], v[142:145], v[204:207], v[28:31]
	v_mfma_f32_16x16x32_bf16 v[20:23], v[150:153], v[204:207], v[20:23]
	v_mfma_f32_16x16x32_bf16 v[12:15], v[142:145], v[212:215], v[12:15]
	v_mfma_f32_16x16x32_bf16 v[4:7], v[150:153], v[212:215], v[4:7]
	v_mfma_f32_16x16x32_bf16 v[64:67], v[146:149], v[178:181], v[64:67]
	v_mfma_f32_16x16x32_bf16 v[56:59], v[154:157], v[178:181], v[56:59]
	v_mfma_f32_16x16x32_bf16 v[44:47], v[146:149], v[200:203], v[44:47]
	v_mfma_f32_16x16x32_bf16 v[36:39], v[154:157], v[200:203], v[36:39]
	v_mfma_f32_16x16x32_bf16 v[28:31], v[146:149], v[208:211], v[28:31]
	v_mfma_f32_16x16x32_bf16 v[20:23], v[154:157], v[208:211], v[20:23]
	v_mfma_f32_16x16x32_bf16 v[12:15], v[146:149], v[216:219], v[12:15]
	v_mfma_f32_16x16x32_bf16 v[4:7], v[154:157], v[216:219], v[4:7]
	s_setprio 1
	s_setprio 2
	v_mfma_f32_16x16x32_bf16 v[60:63], v[158:161], v[174:177], v[60:63]
	v_mfma_f32_16x16x32_bf16 v[52:55], v[166:169], v[174:177], v[52:55]
	v_mfma_f32_16x16x32_bf16 v[40:43], v[158:161], v[196:199], v[40:43]
	v_mfma_f32_16x16x32_bf16 v[32:35], v[166:169], v[196:199], v[32:35]
	v_mfma_f32_16x16x32_bf16 v[24:27], v[158:161], v[204:207], v[24:27]
	v_mfma_f32_16x16x32_bf16 v[16:19], v[166:169], v[204:207], v[16:19]
	v_mfma_f32_16x16x32_bf16 v[8:11], v[158:161], v[212:215], v[8:11]
	v_mfma_f32_16x16x32_bf16 v[0:3], v[166:169], v[212:215], v[0:3]
	v_mfma_f32_16x16x32_bf16 v[60:63], v[162:165], v[178:181], v[60:63]
	v_mfma_f32_16x16x32_bf16 v[52:55], v[170:173], v[178:181], v[52:55]
	v_mfma_f32_16x16x32_bf16 v[40:43], v[162:165], v[200:203], v[40:43]
	v_mfma_f32_16x16x32_bf16 v[32:35], v[170:173], v[200:203], v[32:35]
	v_mfma_f32_16x16x32_bf16 v[24:27], v[162:165], v[208:211], v[24:27]
	v_mfma_f32_16x16x32_bf16 v[16:19], v[170:173], v[208:211], v[16:19]
	v_mfma_f32_16x16x32_bf16 v[8:11], v[162:165], v[216:219], v[8:11]
	v_mfma_f32_16x16x32_bf16 v[0:3], v[170:173], v[216:219], v[0:3]
	s_setprio 1
	s_barrier
	s_add_i32 s65, 0, 0x18000
	s_add_i32 s72, 0, 0x1c000
	v_add_u32_e32 v154, s65, v140
	v_add_u32_e32 v170, s72, v140
	ds_read_b128 v[142:145], v154
	ds_read_b128 v[146:149], v154 offset:1024
	ds_read_b128 v[150:153], v154 offset:2048
	ds_read_b128 v[154:157], v154 offset:3072
	ds_read_b128 v[158:161], v170
	ds_read_b128 v[162:165], v170 offset:1024
	ds_read_b128 v[166:169], v170 offset:2048
	ds_read_b128 v[170:173], v170 offset:3072
	s_add_u32 s50, s50, 0x40000
	s_addc_u32 s51, s51, 0
	s_mov_b32 m0, s17
	v_lshl_add_u64 v[226:227], s[50:51], 0, v[134:135]
	ds_read_b128 v[174:177], v141 offset:32768
	ds_read_b128 v[178:181], v141 offset:33792
	ds_read_b128 v[196:199], v141 offset:34816
	ds_read_b128 v[200:203], v141 offset:35840
	ds_read_b128 v[204:207], v141 offset:36864
	ds_read_b128 v[208:211], v141 offset:37888
	ds_read_b128 v[212:215], v141 offset:38912
	ds_read_b128 v[216:219], v141 offset:39936
	global_load_lds_dwordx4 v[226:227], off
	v_lshl_add_u64 v[226:227], s[50:51], 0, v[132:133]
	s_mov_b32 m0, s18
	s_nop 0
	global_load_lds_dwordx4 v[226:227], off
	s_waitcnt vmcnt(8)
	s_waitcnt lgkmcnt(0)
	s_barrier
	s_setprio 2
	s_waitcnt lgkmcnt(0)
	v_mfma_f32_16x16x32_bf16 v[128:131], v[142:145], v[174:177], v[128:131]
	v_mfma_f32_16x16x32_bf16 v[120:123], v[150:153], v[174:177], v[120:123]
	v_mfma_f32_16x16x32_bf16 v[112:115], v[142:145], v[196:199], v[112:115]
	v_mfma_f32_16x16x32_bf16 v[104:107], v[150:153], v[196:199], v[104:107]
	v_mfma_f32_16x16x32_bf16 v[96:99], v[142:145], v[204:207], v[96:99]
	v_mfma_f32_16x16x32_bf16 v[88:91], v[150:153], v[204:207], v[88:91]
	v_mfma_f32_16x16x32_bf16 v[80:83], v[142:145], v[212:215], v[80:83]
	v_mfma_f32_16x16x32_bf16 v[72:75], v[150:153], v[212:215], v[72:75]
	v_mfma_f32_16x16x32_bf16 v[128:131], v[146:149], v[178:181], v[128:131]
	v_mfma_f32_16x16x32_bf16 v[120:123], v[154:157], v[178:181], v[120:123]
	v_mfma_f32_16x16x32_bf16 v[112:115], v[146:149], v[200:203], v[112:115]
	v_mfma_f32_16x16x32_bf16 v[104:107], v[154:157], v[200:203], v[104:107]
	v_mfma_f32_16x16x32_bf16 v[96:99], v[146:149], v[208:211], v[96:99]
	v_mfma_f32_16x16x32_bf16 v[88:91], v[154:157], v[208:211], v[88:91]
	v_mfma_f32_16x16x32_bf16 v[80:83], v[146:149], v[216:219], v[80:83]
	v_mfma_f32_16x16x32_bf16 v[72:75], v[154:157], v[216:219], v[72:75]
	s_setprio 1
	s_setprio 2
	v_mfma_f32_16x16x32_bf16 v[124:127], v[158:161], v[174:177], v[124:127]
	v_mfma_f32_16x16x32_bf16 v[116:119], v[166:169], v[174:177], v[116:119]
	v_mfma_f32_16x16x32_bf16 v[108:111], v[158:161], v[196:199], v[108:111]
	v_mfma_f32_16x16x32_bf16 v[100:103], v[166:169], v[196:199], v[100:103]
	v_mfma_f32_16x16x32_bf16 v[92:95], v[158:161], v[204:207], v[92:95]
	v_mfma_f32_16x16x32_bf16 v[84:87], v[166:169], v[204:207], v[84:87]
	v_mfma_f32_16x16x32_bf16 v[76:79], v[158:161], v[212:215], v[76:79]
	v_mfma_f32_16x16x32_bf16 v[68:71], v[166:169], v[212:215], v[68:71]
	v_mfma_f32_16x16x32_bf16 v[124:127], v[162:165], v[178:181], v[124:127]
	v_mfma_f32_16x16x32_bf16 v[116:119], v[170:173], v[178:181], v[116:119]
	v_mfma_f32_16x16x32_bf16 v[108:111], v[162:165], v[200:203], v[108:111]
	v_mfma_f32_16x16x32_bf16 v[100:103], v[170:173], v[200:203], v[100:103]
	v_mfma_f32_16x16x32_bf16 v[92:95], v[162:165], v[208:211], v[92:95]
	v_mfma_f32_16x16x32_bf16 v[84:87], v[170:173], v[208:211], v[84:87]
	v_mfma_f32_16x16x32_bf16 v[76:79], v[162:165], v[216:219], v[76:79]
	v_mfma_f32_16x16x32_bf16 v[68:71], v[170:173], v[216:219], v[68:71]
	s_setprio 1
	s_barrier
	s_add_i32 s50, s65, s11
	v_lshl_add_u64 v[182:183], v[182:183], 0, s[58:59]
	s_mov_b32 m0, s50
	ds_read_b128 v[174:177], v141 offset:49152
	ds_read_b128 v[178:181], v141 offset:50176
	ds_read_b128 v[196:199], v141 offset:51200
	ds_read_b128 v[200:203], v141 offset:52224
	ds_read_b128 v[204:207], v141 offset:53248
	ds_read_b128 v[208:211], v141 offset:54272
	ds_read_b128 v[212:215], v141 offset:55296
	ds_read_b128 v[216:219], v141 offset:56320
	global_load_lds_dwordx4 v[182:183], off
	s_add_i32 m0, s50, 0x2000
	s_add_u32 s26, s26, 0x40080
	v_lshl_add_u64 v[182:183], v[220:221], 0, s[58:59]
	s_addc_u32 s27, s27, 0
	s_add_i32 s50, s72, s11
	global_load_lds_dwordx4 v[182:183], off
	v_lshl_add_u64 v[182:183], s[26:27], 0, v[50:51]
	s_mov_b32 m0, s50
	s_nop 0
	global_load_lds_dwordx4 v[182:183], off
	v_lshl_add_u64 v[182:183], s[26:27], 0, v[48:49]
	s_add_i32 m0, s50, 0x2000
	s_nop 0
	global_load_lds_dwordx4 v[182:183], off
	v_lshl_add_u64 v[182:183], v[222:223], 0, s[58:59]
	s_mov_b32 m0, s21
	s_nop 0
	global_load_lds_dwordx4 v[182:183], off
	v_lshl_add_u64 v[182:183], v[224:225], 0, s[58:59]
	s_mov_b32 m0, s22
	s_nop 0
	global_load_lds_dwordx4 v[182:183], off
	s_waitcnt vmcnt(8)
	s_waitcnt lgkmcnt(0)
	s_barrier
	s_setprio 2
	s_waitcnt lgkmcnt(0)
	v_mfma_f32_16x16x32_bf16 v[64:67], v[142:145], v[174:177], v[64:67]
	v_mfma_f32_16x16x32_bf16 v[56:59], v[150:153], v[174:177], v[56:59]
	v_mfma_f32_16x16x32_bf16 v[44:47], v[142:145], v[196:199], v[44:47]
	v_mfma_f32_16x16x32_bf16 v[36:39], v[150:153], v[196:199], v[36:39]
	v_mfma_f32_16x16x32_bf16 v[28:31], v[142:145], v[204:207], v[28:31]
	v_mfma_f32_16x16x32_bf16 v[20:23], v[150:153], v[204:207], v[20:23]
	v_mfma_f32_16x16x32_bf16 v[12:15], v[142:145], v[212:215], v[12:15]
	v_mfma_f32_16x16x32_bf16 v[4:7], v[150:153], v[212:215], v[4:7]
	v_mfma_f32_16x16x32_bf16 v[64:67], v[146:149], v[178:181], v[64:67]
	v_mfma_f32_16x16x32_bf16 v[56:59], v[154:157], v[178:181], v[56:59]
	v_mfma_f32_16x16x32_bf16 v[44:47], v[146:149], v[200:203], v[44:47]
	v_mfma_f32_16x16x32_bf16 v[36:39], v[154:157], v[200:203], v[36:39]
	v_mfma_f32_16x16x32_bf16 v[28:31], v[146:149], v[208:211], v[28:31]
	v_mfma_f32_16x16x32_bf16 v[20:23], v[154:157], v[208:211], v[20:23]
	v_mfma_f32_16x16x32_bf16 v[12:15], v[146:149], v[216:219], v[12:15]
	v_mfma_f32_16x16x32_bf16 v[4:7], v[154:157], v[216:219], v[4:7]
	s_setprio 1
	s_setprio 2
	v_mfma_f32_16x16x32_bf16 v[60:63], v[158:161], v[174:177], v[60:63]
	v_mfma_f32_16x16x32_bf16 v[52:55], v[166:169], v[174:177], v[52:55]
	v_mfma_f32_16x16x32_bf16 v[40:43], v[158:161], v[196:199], v[40:43]
	v_mfma_f32_16x16x32_bf16 v[32:35], v[166:169], v[196:199], v[32:35]
	v_mfma_f32_16x16x32_bf16 v[24:27], v[158:161], v[204:207], v[24:27]
	v_mfma_f32_16x16x32_bf16 v[16:19], v[166:169], v[204:207], v[16:19]
	v_mfma_f32_16x16x32_bf16 v[8:11], v[158:161], v[212:215], v[8:11]
	v_mfma_f32_16x16x32_bf16 v[0:3], v[166:169], v[212:215], v[0:3]
	v_mfma_f32_16x16x32_bf16 v[60:63], v[162:165], v[178:181], v[60:63]
	v_mfma_f32_16x16x32_bf16 v[52:55], v[170:173], v[178:181], v[52:55]
	v_mfma_f32_16x16x32_bf16 v[40:43], v[162:165], v[200:203], v[40:43]
	v_mfma_f32_16x16x32_bf16 v[32:35], v[170:173], v[200:203], v[32:35]
	v_mfma_f32_16x16x32_bf16 v[24:27], v[162:165], v[208:211], v[24:27]
	v_mfma_f32_16x16x32_bf16 v[16:19], v[170:173], v[208:211], v[16:19]
	v_mfma_f32_16x16x32_bf16 v[8:11], v[162:165], v[216:219], v[8:11]
	v_mfma_f32_16x16x32_bf16 v[0:3], v[170:173], v[216:219], v[0:3]
	s_setprio 1
	s_barrier
	s_add_i32 s64, s64, 2
	s_add_u32 s48, s48, 0x100
	s_addc_u32 s49, s49, 0
	s_add_u32 s52, s52, 0x100
	s_addc_u32 s53, s53, 0
	s_cmp_gt_u32 s64, 13
	s_cbranch_scc0 .Lgk2_1706
	s_setprio 0
.Lgk_join:
	s_and_b64 vcc, exec, s[6:7]
	s_cbranch_vccz .LBB0_1709
	s_barrier
